# GEMM1 mainloop loop-edge rotation: back-edge scalars and the DMA address math of phases 1, 2 and 4 moved in front of the preceding barrier (strategy 9: loop-edge edit)
# baseline (speedup 1.0000x reference)
;     __device__ bool next(int i, Unit& u) const { if (i != 0) return false; u.pm = pm; u.pn = pn; return true; }
;     __device__ bool next(int i, Unit& u) const { const int L = i * G + c; if (L >= 256) return false; u.pm = L; u.pn = L >> 6; return true; }
;     __device__ bool next(int i, Unit& u) const { Unit t; if (!so.next(i >> 2, t)) return false; const int b = i & 3; u.pm = b * 64 + t.pm; u.pn = b * 8 + t.pn; return true; }
; #define PG8_STAGE(bufoff, gbase, voff) do { _Pragma("unroll") for (int _i = 0; _i < 2; ++_i) \
;         __builtin_amdgcn_global_load_lds((const unsigned*)((const char*)(gbase) + (voff)[_i]), (LAS unsigned*)(lds + (bufoff) + ldsw + _i * 8192), 16, 0, 0); } while (0)
; #define PG8_LDA(dst, b, h) do { _Pragma("unroll") for (int m = 0; m < 4; ++m) _Pragma("unroll") for (int k = 0; k < 2; ++k) dst[m][k] = *(const LAS bf16x8*)(lds + PG8_SA(b, h) + aoff + m * 2048 + k * 1024); } while (0)
; #define PG8_WAIT_V(n) asm volatile("s_waitcnt vmcnt(" #n ")" ::: "memory")
; template <bool ALIGN_EPI, bool SP2, class Epi, class Sched>
; __device__ __forceinline__ void gemm_phase(LAS unsigned char* lds, const Gemm g, const Sched& S, const Epi& E) {
;     ...
;     f32x4 acc[2][2][4][2];
; #pragma unroll
;     for (int a = 0; a < 2; ++a)
; #pragma unroll
;         for (int b = 0; b < 2; ++b)
; #pragma unroll
;             for (int m = 0; m < 4; ++m)
; #pragma unroll
;                 for (int n = 0; n < 2; ++n) acc[a][b][m][n] = (f32x4){0.f, 0.f, 0.f, 0.f};
;     ...
;     for (;;) {
;         const bool has_next = S.next(ui + 1, nxt);
;         const char* nA = has_next ? (const char*)g.A + (size_t)nxt.pm * tstep : cA; const char* nB = has_next ? (const char*)g.Bt + (size_t)nxt.pn * tstep : cB;
;         for (int t = 0; t < nt; t += 2) {
;             const bool last = (t == nt - 2);
;             const char* a1 = cA + (size_t)(t + 1) * kstep;
;             const char* a2 = last ? nA : cA + (size_t)(t + 2) * kstep; const char* b2 = last ? nB : cB + (size_t)(t + 2) * kstep;
;             const char* a3 = a2 + kstep; const char* b3 = b2 + kstep;
;             if constexpr (SP2) {
;             PG8_STAGE(PG8_SA(1, 1), a1 + hstep, voffA); PG8_SCHED; PG8_LDB(B0, 0, 0); PG8_LDB(B1, 0, 1); PG8_SCHED; PG8_LDA(At, 0, 0);
;             PG8_WAIT_V(8); PG8_WAIT_L(0); PG8_BAR; PG8_MMA(0, 0, At, B0); PG8_MMA(0, 1, At, B1); PG8_BAR; PG8_SCHED;
.LBB0_233:
	v_mov_b32_e32 v117, 0
	s_andn2_b64 vcc, exec, s[38:39]
	v_mov_b32_e32 v116, v117
	v_mov_b32_e32 v115, v117
	v_mov_b32_e32 v114, v117
	v_mov_b32_e32 v129, v117
	v_mov_b32_e32 v128, v117
	v_mov_b32_e32 v127, v117
	v_mov_b32_e32 v126, v117
	v_mov_b32_e32 v101, v117
	v_mov_b32_e32 v100, v117
	v_mov_b32_e32 v99, v117
	v_mov_b32_e32 v98, v117
	v_mov_b32_e32 v113, v117
	v_mov_b32_e32 v112, v117
	v_mov_b32_e32 v111, v117
	v_mov_b32_e32 v110, v117
	v_mov_b32_e32 v85, v117
	v_mov_b32_e32 v84, v117
	v_mov_b32_e32 v83, v117
	v_mov_b32_e32 v82, v117
	v_mov_b32_e32 v97, v117
	v_mov_b32_e32 v96, v117
	v_mov_b32_e32 v95, v117
	v_mov_b32_e32 v94, v117
	v_mov_b32_e32 v69, v117
	v_mov_b32_e32 v68, v117
	v_mov_b32_e32 v67, v117
	v_mov_b32_e32 v66, v117
	v_mov_b32_e32 v81, v117
	v_mov_b32_e32 v80, v117
	v_mov_b32_e32 v79, v117
	v_mov_b32_e32 v78, v117
	v_mov_b32_e32 v125, v117
	v_mov_b32_e32 v124, v117
	v_mov_b32_e32 v123, v117
	v_mov_b32_e32 v122, v117
	v_mov_b32_e32 v121, v117
	v_mov_b32_e32 v120, v117
	v_mov_b32_e32 v119, v117
	v_mov_b32_e32 v118, v117
	v_mov_b32_e32 v109, v117
	v_mov_b32_e32 v108, v117
	v_mov_b32_e32 v107, v117
	v_mov_b32_e32 v106, v117
	v_mov_b32_e32 v105, v117
	v_mov_b32_e32 v104, v117
	v_mov_b32_e32 v103, v117
	v_mov_b32_e32 v102, v117
	v_mov_b32_e32 v93, v117
	v_mov_b32_e32 v92, v117
	v_mov_b32_e32 v91, v117
	v_mov_b32_e32 v90, v117
	v_mov_b32_e32 v89, v117
	v_mov_b32_e32 v88, v117
	v_mov_b32_e32 v87, v117
	v_mov_b32_e32 v86, v117
	v_mov_b32_e32 v77, v117
	v_mov_b32_e32 v76, v117
	v_mov_b32_e32 v75, v117
	v_mov_b32_e32 v74, v117
	v_mov_b32_e32 v73, v117
	v_mov_b32_e32 v72, v117
	v_mov_b32_e32 v71, v117
	v_mov_b32_e32 v70, v117
	v_mov_b32_e32 v53, v117
	v_mov_b32_e32 v52, v117
	v_mov_b32_e32 v51, v117
	v_mov_b32_e32 v50, v117
	v_mov_b32_e32 v65, v117
	v_mov_b32_e32 v64, v117
	v_mov_b32_e32 v63, v117
	v_mov_b32_e32 v62, v117
	v_mov_b32_e32 v37, v117
	v_mov_b32_e32 v36, v117
	v_mov_b32_e32 v35, v117
	v_mov_b32_e32 v34, v117
	v_mov_b32_e32 v49, v117
	v_mov_b32_e32 v48, v117
	v_mov_b32_e32 v47, v117
	v_mov_b32_e32 v46, v117
	v_mov_b32_e32 v21, v117
	v_mov_b32_e32 v20, v117
	v_mov_b32_e32 v19, v117
	v_mov_b32_e32 v18, v117
	v_mov_b32_e32 v33, v117
	v_mov_b32_e32 v32, v117
	v_mov_b32_e32 v31, v117
	v_mov_b32_e32 v30, v117
	v_mov_b32_e32 v5, v117
	v_mov_b32_e32 v4, v117
	v_mov_b32_e32 v3, v117
	v_mov_b32_e32 v2, v117
	v_mov_b32_e32 v17, v117
	v_mov_b32_e32 v16, v117
	v_mov_b32_e32 v15, v117
	v_mov_b32_e32 v14, v117
	v_mov_b32_e32 v61, v117
	v_mov_b32_e32 v60, v117
	v_mov_b32_e32 v59, v117
	v_mov_b32_e32 v58, v117
	v_mov_b32_e32 v57, v117
	v_mov_b32_e32 v56, v117
	v_mov_b32_e32 v55, v117
	v_mov_b32_e32 v54, v117
	v_mov_b32_e32 v45, v117
	v_mov_b32_e32 v44, v117
	v_mov_b32_e32 v43, v117
	v_mov_b32_e32 v42, v117
	v_mov_b32_e32 v41, v117
	v_mov_b32_e32 v40, v117
	v_mov_b32_e32 v39, v117
	v_mov_b32_e32 v38, v117
	v_mov_b32_e32 v29, v117
	v_mov_b32_e32 v28, v117
	v_mov_b32_e32 v27, v117
	v_mov_b32_e32 v26, v117
	v_mov_b32_e32 v25, v117
	v_mov_b32_e32 v24, v117
	v_mov_b32_e32 v23, v117
	v_mov_b32_e32 v22, v117
	v_mov_b32_e32 v13, v117
	v_mov_b32_e32 v12, v117
	v_mov_b32_e32 v11, v117
	v_mov_b32_e32 v10, v117
	v_mov_b32_e32 v9, v117
	v_mov_b32_e32 v8, v117
	v_mov_b32_e32 v7, v117
	v_mov_b32_e32 v6, v117
	s_cbranch_vccnz .LBB0_236
	s_add_u32 s42, s90, 0x80
	s_addc_u32 s43, s91, 0
	s_add_u32 s24, s44, 0x100
	v_mov_b32_e32 v6, 0
	s_addc_u32 s71, s45, 0
	s_mov_b32 s44, 0
	v_lshl_add_u64 v[162:163], s[42:43], 0, v[138:139]
	v_lshl_add_u64 v[230:231], s[42:43], 0, v[148:149]
.LBB0_235:
	s_add_i32 s88, s44, 2
	s_add_u32 s89, s42, 0x80
	s_addc_u32 s45, s43, 0
	s_add_i32 m0, s95, 0xc000
	s_add_i32 s90, s95, 0xe000
	global_load_lds_dwordx4 v[162:163], off
	s_mov_b32 m0, s90
	s_cmp_eq_u32 s65, s44
	global_load_lds_dwordx4 v[230:231], off
	s_cselect_b32 s44, s48, s89
	s_cselect_b32 s45, s49, s45
	s_cselect_b32 s91, s87, s71
	s_cselect_b32 s90, s86, s24
	s_add_i32 s89, 0, 0x10000
	v_add_u32_e32 v0, s89, v165
	s_add_i32 s92, 0, 0x14000
	ds_read_b128 v[150:153], v0
	ds_read_b128 v[154:157], v0 offset:1024
	ds_read_b128 v[158:161], v0 offset:2048
	ds_read_b128 v[178:181], v0 offset:3072
	v_add_u32_e32 v0, s92, v165
	ds_read_b128 v[182:185], v0
	ds_read_b128 v[186:189], v0 offset:1024
	ds_read_b128 v[190:193], v0 offset:2048
	ds_read_b128 v[194:197], v0 offset:3072
	ds_read_b128 v[198:201], v176
	ds_read_b128 v[202:205], v176 offset:1024
	ds_read_b128 v[206:209], v176 offset:2048
	ds_read_b128 v[210:213], v176 offset:3072
	ds_read_b128 v[214:217], v176 offset:4096
	ds_read_b128 v[218:221], v176 offset:5120
	ds_read_b128 v[222:225], v176 offset:6144
	ds_read_b128 v[226:229], v176 offset:7168
	s_waitcnt vmcnt(8)
	s_waitcnt lgkmcnt(0)
	s_barrier
; #define PG8_STAGE(bufoff, gbase, voff) do { _Pragma("unroll") for (int _i = 0; _i < 2; ++_i) \
;         __builtin_amdgcn_global_load_lds((const unsigned*)((const char*)(gbase) + (voff)[_i]), (LAS unsigned*)(lds + (bufoff) + ldsw + _i * 8192), 16, 0, 0); } while (0)
; #define PG8_LDA(dst, b, h) do { _Pragma("unroll") for (int m = 0; m < 4; ++m) _Pragma("unroll") for (int k = 0; k < 2; ++k) dst[m][k] = *(const LAS bf16x8*)(lds + PG8_SA(b, h) + aoff + m * 2048 + k * 1024); } while (0)
; #define PG8_MMA(ai, bj, At, Bt) do { __builtin_amdgcn_s_setprio(1); _Pragma("unroll") for (int m = 0; m < 4; ++m) _Pragma("unroll") for (int n = 0; n < 2; ++n) _Pragma("unroll") for (int k = 0; k < 2; ++k) \
;         acc[ai][bj][m][n] = __builtin_amdgcn_mfma_f32_16x16x32_bf16(Bt[n][k], At[m][k], acc[ai][bj][m][n], 0, 0, 0); __builtin_amdgcn_s_setprio(0); } while (0)
; #define PG8_WAIT_V(n) asm volatile("s_waitcnt vmcnt(" #n ")" ::: "memory")
; #define PG8_WAIT_L(n) asm volatile("s_waitcnt lgkmcnt(" #n ")" ::: "memory")
; #define PG8_BAR __builtin_amdgcn_s_barrier()
; #define PG8_SCHED __builtin_amdgcn_sched_barrier(0)
; template <bool ALIGN_EPI, bool SP2, class Epi, class Sched>
; __device__ __forceinline__ void gemm_phase(LAS unsigned char* lds, const Gemm g, const Sched& S, const Epi& E) {
;     ...
;             PG8_WAIT_V(8); PG8_WAIT_L(0); PG8_BAR; PG8_MMA(0, 0, At, B0); PG8_MMA(0, 1, At, B1); PG8_BAR; PG8_SCHED;
;             PG8_STAGE(PG8_SB(0, 0), b2, voffB); PG8_STAGE(PG8_SB(0, 1), b2 + hstep, voffB); PG8_STAGE(PG8_SA(0, 0), a2, voffA); PG8_SCHED; PG8_LDA(At, 0, 1);
;             PG8_WAIT_V(8); PG8_WAIT_L(0); PG8_BAR; PG8_MMA(1, 0, At, B0); PG8_MMA(1, 1, At, B1); PG8_BAR; PG8_SCHED;
	s_setprio 1
	s_waitcnt lgkmcnt(0)
	v_mfma_f32_16x16x32_bf16 v[114:117], v[150:153], v[198:201], v[114:117]
	v_mfma_f32_16x16x32_bf16 v[126:129], v[158:161], v[198:201], v[126:129]
	v_mfma_f32_16x16x32_bf16 v[98:101], v[150:153], v[206:209], v[98:101]
	v_mfma_f32_16x16x32_bf16 v[110:113], v[158:161], v[206:209], v[110:113]
	v_mfma_f32_16x16x32_bf16 v[82:85], v[150:153], v[214:217], v[82:85]
	v_mfma_f32_16x16x32_bf16 v[94:97], v[158:161], v[214:217], v[94:97]
	v_mfma_f32_16x16x32_bf16 v[66:69], v[150:153], v[222:225], v[66:69]
	v_mfma_f32_16x16x32_bf16 v[78:81], v[158:161], v[222:225], v[78:81]
	v_mfma_f32_16x16x32_bf16 v[114:117], v[154:157], v[202:205], v[114:117]
	v_mfma_f32_16x16x32_bf16 v[126:129], v[178:181], v[202:205], v[126:129]
	v_mfma_f32_16x16x32_bf16 v[98:101], v[154:157], v[210:213], v[98:101]
	v_mfma_f32_16x16x32_bf16 v[110:113], v[178:181], v[210:213], v[110:113]
	v_mfma_f32_16x16x32_bf16 v[82:85], v[154:157], v[218:221], v[82:85]
	v_mfma_f32_16x16x32_bf16 v[94:97], v[178:181], v[218:221], v[94:97]
	v_mfma_f32_16x16x32_bf16 v[66:69], v[154:157], v[226:229], v[66:69]
	v_mfma_f32_16x16x32_bf16 v[78:81], v[178:181], v[226:229], v[78:81]
	s_setprio 0
	s_setprio 1
	v_mfma_f32_16x16x32_bf16 v[122:125], v[182:185], v[198:201], v[122:125]
	v_mfma_f32_16x16x32_bf16 v[118:121], v[190:193], v[198:201], v[118:121]
	v_mfma_f32_16x16x32_bf16 v[106:109], v[182:185], v[206:209], v[106:109]
	v_mfma_f32_16x16x32_bf16 v[102:105], v[190:193], v[206:209], v[102:105]
	v_mfma_f32_16x16x32_bf16 v[90:93], v[182:185], v[214:217], v[90:93]
	v_mfma_f32_16x16x32_bf16 v[86:89], v[190:193], v[214:217], v[86:89]
	v_mfma_f32_16x16x32_bf16 v[74:77], v[182:185], v[222:225], v[74:77]
	v_mfma_f32_16x16x32_bf16 v[70:73], v[190:193], v[222:225], v[70:73]
	v_mfma_f32_16x16x32_bf16 v[122:125], v[186:189], v[202:205], v[122:125]
	v_mfma_f32_16x16x32_bf16 v[118:121], v[194:197], v[202:205], v[118:121]
	v_mfma_f32_16x16x32_bf16 v[106:109], v[186:189], v[210:213], v[106:109]
	v_mfma_f32_16x16x32_bf16 v[102:105], v[194:197], v[210:213], v[102:105]
	v_mfma_f32_16x16x32_bf16 v[90:93], v[186:189], v[218:221], v[90:93]
	v_mfma_f32_16x16x32_bf16 v[86:89], v[194:197], v[218:221], v[86:89]
	v_mfma_f32_16x16x32_bf16 v[74:77], v[186:189], v[226:229], v[74:77]
	v_mfma_f32_16x16x32_bf16 v[70:73], v[194:197], v[226:229], v[70:73]
	s_setprio 0
	v_lshl_add_u64 v[162:163], s[90:91], 0, v[132:133]
	v_lshl_add_u64 v[230:231], s[90:91], 0, v[136:137]
	s_add_u32 s90, s90, s14
	s_addc_u32 s91, s91, s15
	v_lshl_add_u64 v[232:233], s[90:91], 0, v[132:133]
	v_lshl_add_u64 v[234:235], s[90:91], 0, v[136:137]
	v_lshl_add_u64 v[236:237], s[44:45], 0, v[130:131]
	v_lshl_add_u64 v[238:239], s[44:45], 0, v[134:135]
	s_add_i32 s89, s89, s94
	s_barrier
	s_mov_b32 m0, s89
	s_nop 0
	global_load_lds_dwordx4 v[162:163], off
	s_add_i32 m0, s89, 0x2000
	s_add_i32 s89, s92, s94
	global_load_lds_dwordx4 v[230:231], off
	s_mov_b32 m0, s89
	s_nop 0
	global_load_lds_dwordx4 v[232:233], off
	s_add_i32 m0, s89, 0x2000
	s_nop 0
	global_load_lds_dwordx4 v[234:235], off
	s_mov_b32 m0, s95
	s_nop 0
	global_load_lds_dwordx4 v[236:237], off
	s_mov_b32 m0, s96
	s_nop 0
	global_load_lds_dwordx4 v[238:239], off
	ds_read_b128 v[198:201], v176 offset:16384
	ds_read_b128 v[202:205], v176 offset:17408
	ds_read_b128 v[206:209], v176 offset:18432
	ds_read_b128 v[210:213], v176 offset:19456
	ds_read_b128 v[214:217], v176 offset:20480
	ds_read_b128 v[218:221], v176 offset:21504
	ds_read_b128 v[222:225], v176 offset:22528
	ds_read_b128 v[226:229], v176 offset:23552
	s_waitcnt vmcnt(8)
	s_waitcnt lgkmcnt(0)
	s_barrier
	s_setprio 1
	s_waitcnt lgkmcnt(0)
	v_mfma_f32_16x16x32_bf16 v[50:53], v[150:153], v[198:201], v[50:53]
	v_mfma_f32_16x16x32_bf16 v[62:65], v[158:161], v[198:201], v[62:65]
	v_mfma_f32_16x16x32_bf16 v[34:37], v[150:153], v[206:209], v[34:37]
	v_mfma_f32_16x16x32_bf16 v[46:49], v[158:161], v[206:209], v[46:49]
	v_mfma_f32_16x16x32_bf16 v[18:21], v[150:153], v[214:217], v[18:21]
	v_mfma_f32_16x16x32_bf16 v[30:33], v[158:161], v[214:217], v[30:33]
	v_mfma_f32_16x16x32_bf16 v[2:5], v[150:153], v[222:225], v[2:5]
	v_mfma_f32_16x16x32_bf16 v[14:17], v[158:161], v[222:225], v[14:17]
	v_mfma_f32_16x16x32_bf16 v[50:53], v[154:157], v[202:205], v[50:53]
	v_mfma_f32_16x16x32_bf16 v[62:65], v[178:181], v[202:205], v[62:65]
	v_mfma_f32_16x16x32_bf16 v[34:37], v[154:157], v[210:213], v[34:37]
	v_mfma_f32_16x16x32_bf16 v[46:49], v[178:181], v[210:213], v[46:49]
	v_mfma_f32_16x16x32_bf16 v[18:21], v[154:157], v[218:221], v[18:21]
	v_mfma_f32_16x16x32_bf16 v[30:33], v[178:181], v[218:221], v[30:33]
	v_mfma_f32_16x16x32_bf16 v[2:5], v[154:157], v[226:229], v[2:5]
	v_mfma_f32_16x16x32_bf16 v[14:17], v[178:181], v[226:229], v[14:17]
	s_setprio 0
	s_setprio 1
	v_mfma_f32_16x16x32_bf16 v[58:61], v[182:185], v[198:201], v[58:61]
	v_mfma_f32_16x16x32_bf16 v[54:57], v[190:193], v[198:201], v[54:57]
	v_mfma_f32_16x16x32_bf16 v[42:45], v[182:185], v[206:209], v[42:45]
	v_mfma_f32_16x16x32_bf16 v[38:41], v[190:193], v[206:209], v[38:41]
	v_mfma_f32_16x16x32_bf16 v[26:29], v[182:185], v[214:217], v[26:29]
	v_mfma_f32_16x16x32_bf16 v[22:25], v[190:193], v[214:217], v[22:25]
	v_mfma_f32_16x16x32_bf16 v[10:13], v[182:185], v[222:225], v[10:13]
	v_mfma_f32_16x16x32_bf16 v[6:9], v[190:193], v[222:225], v[6:9]
	v_mfma_f32_16x16x32_bf16 v[58:61], v[186:189], v[202:205], v[58:61]
	v_mfma_f32_16x16x32_bf16 v[54:57], v[194:197], v[202:205], v[54:57]
	v_mfma_f32_16x16x32_bf16 v[42:45], v[186:189], v[210:213], v[42:45]
	v_mfma_f32_16x16x32_bf16 v[38:41], v[194:197], v[210:213], v[38:41]
	v_mfma_f32_16x16x32_bf16 v[26:29], v[186:189], v[218:221], v[26:29]
	v_mfma_f32_16x16x32_bf16 v[22:25], v[194:197], v[218:221], v[22:25]
	v_mfma_f32_16x16x32_bf16 v[10:13], v[186:189], v[226:229], v[10:13]
	v_mfma_f32_16x16x32_bf16 v[6:9], v[194:197], v[226:229], v[6:9]
	s_setprio 0
	s_barrier
; #define PG8_STAGE(bufoff, gbase, voff) do { _Pragma("unroll") for (int _i = 0; _i < 2; ++_i) \
;         __builtin_amdgcn_global_load_lds((const unsigned*)((const char*)(gbase) + (voff)[_i]), (LAS unsigned*)(lds + (bufoff) + ldsw + _i * 8192), 16, 0, 0); } while (0)
; #define PG8_LDA(dst, b, h) do { _Pragma("unroll") for (int m = 0; m < 4; ++m) _Pragma("unroll") for (int k = 0; k < 2; ++k) dst[m][k] = *(const LAS bf16x8*)(lds + PG8_SA(b, h) + aoff + m * 2048 + k * 1024); } while (0)
; #define PG8_LDB(dst, b, h) do { _Pragma("unroll") for (int n = 0; n < 2; ++n) _Pragma("unroll") for (int k = 0; k < 2; ++k) dst[n][k] = *(const LAS bf16x8*)(lds + PG8_SB(b, h) + boff + n * 2048 + k * 1024); } while (0)
; #define PG8_MMA(ai, bj, At, Bt) do { __builtin_amdgcn_s_setprio(1); _Pragma("unroll") for (int m = 0; m < 4; ++m) _Pragma("unroll") for (int n = 0; n < 2; ++n) _Pragma("unroll") for (int k = 0; k < 2; ++k) \
;         acc[ai][bj][m][n] = __builtin_amdgcn_mfma_f32_16x16x32_bf16(Bt[n][k], At[m][k], acc[ai][bj][m][n], 0, 0, 0); __builtin_amdgcn_s_setprio(0); } while (0)
; #define PG8_WAIT_V(n) asm volatile("s_waitcnt vmcnt(" #n ")" ::: "memory")
; #define PG8_WAIT_L(n) asm volatile("s_waitcnt lgkmcnt(" #n ")" ::: "memory")
; #define PG8_BAR __builtin_amdgcn_s_barrier()
; #define PG8_SCHED __builtin_amdgcn_sched_barrier(0)
; template <bool ALIGN_EPI, bool SP2, class Epi, class Sched>
; __device__ __forceinline__ void gemm_phase(LAS unsigned char* lds, const Gemm g, const Sched& S, const Epi& E) {
;     ...
;             PG8_STAGE(PG8_SA(0, 1), a2 + hstep, voffA); PG8_SCHED; PG8_LDB(B0, 1, 0); PG8_LDB(B1, 1, 1); PG8_SCHED; PG8_LDA(At, 1, 0);
;             PG8_WAIT_V(8); PG8_WAIT_L(0); PG8_BAR; PG8_MMA(0, 0, At, B0); PG8_MMA(0, 1, At, B1); PG8_BAR; PG8_SCHED;
;             PG8_STAGE(PG8_SB(1, 0), b3, voffB); PG8_STAGE(PG8_SB(1, 1), b3 + hstep, voffB); PG8_STAGE(PG8_SA(1, 0), a3, voffA); PG8_SCHED; PG8_LDA(At, 1, 1);
	s_add_u32 s44, s44, s14
	s_addc_u32 s45, s45, s15
	s_mov_b32 m0, s97
	v_lshl_add_u64 v[150:151], s[44:45], 0, v[130:131]
	global_load_lds_dwordx4 v[150:151], off
	v_lshl_add_u64 v[150:151], s[44:45], 0, v[134:135]
	s_mov_b32 m0, s61
	s_nop 0
	global_load_lds_dwordx4 v[150:151], off
	s_add_i32 s44, 0, 0x18000
	v_add_u32_e32 v0, s44, v165
	s_add_i32 s45, 0, 0x1c000
	ds_read_b128 v[150:153], v0
	ds_read_b128 v[154:157], v0 offset:1024
	ds_read_b128 v[158:161], v0 offset:2048
	ds_read_b128 v[178:181], v0 offset:3072
	v_add_u32_e32 v0, s45, v165
	ds_read_b128 v[182:185], v0
	ds_read_b128 v[186:189], v0 offset:1024
	ds_read_b128 v[190:193], v0 offset:2048
	ds_read_b128 v[194:197], v0 offset:3072
	ds_read_b128 v[198:201], v176 offset:32768
	ds_read_b128 v[202:205], v176 offset:33792
	ds_read_b128 v[206:209], v176 offset:34816
	ds_read_b128 v[210:213], v176 offset:35840
	ds_read_b128 v[214:217], v176 offset:36864
	ds_read_b128 v[218:221], v176 offset:37888
	ds_read_b128 v[222:225], v176 offset:38912
	ds_read_b128 v[226:229], v176 offset:39936
	s_waitcnt vmcnt(8)
	s_waitcnt lgkmcnt(0)
	s_barrier
	s_setprio 1
	s_waitcnt lgkmcnt(0)
	v_mfma_f32_16x16x32_bf16 v[114:117], v[150:153], v[198:201], v[114:117]
	v_mfma_f32_16x16x32_bf16 v[126:129], v[158:161], v[198:201], v[126:129]
	v_mfma_f32_16x16x32_bf16 v[98:101], v[150:153], v[206:209], v[98:101]
	v_mfma_f32_16x16x32_bf16 v[110:113], v[158:161], v[206:209], v[110:113]
	v_mfma_f32_16x16x32_bf16 v[82:85], v[150:153], v[214:217], v[82:85]
	v_mfma_f32_16x16x32_bf16 v[94:97], v[158:161], v[214:217], v[94:97]
	v_mfma_f32_16x16x32_bf16 v[66:69], v[150:153], v[222:225], v[66:69]
	v_mfma_f32_16x16x32_bf16 v[78:81], v[158:161], v[222:225], v[78:81]
	v_mfma_f32_16x16x32_bf16 v[114:117], v[154:157], v[202:205], v[114:117]
	v_mfma_f32_16x16x32_bf16 v[126:129], v[178:181], v[202:205], v[126:129]
	v_mfma_f32_16x16x32_bf16 v[98:101], v[154:157], v[210:213], v[98:101]
	v_mfma_f32_16x16x32_bf16 v[110:113], v[178:181], v[210:213], v[110:113]
	v_mfma_f32_16x16x32_bf16 v[82:85], v[154:157], v[218:221], v[82:85]
	v_mfma_f32_16x16x32_bf16 v[94:97], v[178:181], v[218:221], v[94:97]
	v_mfma_f32_16x16x32_bf16 v[66:69], v[154:157], v[226:229], v[66:69]
	v_mfma_f32_16x16x32_bf16 v[78:81], v[178:181], v[226:229], v[78:81]
	s_setprio 0
	s_setprio 1
	v_mfma_f32_16x16x32_bf16 v[122:125], v[182:185], v[198:201], v[122:125]
	v_mfma_f32_16x16x32_bf16 v[118:121], v[190:193], v[198:201], v[118:121]
	v_mfma_f32_16x16x32_bf16 v[106:109], v[182:185], v[206:209], v[106:109]
	v_mfma_f32_16x16x32_bf16 v[102:105], v[190:193], v[206:209], v[102:105]
	v_mfma_f32_16x16x32_bf16 v[90:93], v[182:185], v[214:217], v[90:93]
	v_mfma_f32_16x16x32_bf16 v[86:89], v[190:193], v[214:217], v[86:89]
	v_mfma_f32_16x16x32_bf16 v[74:77], v[182:185], v[222:225], v[74:77]
	v_mfma_f32_16x16x32_bf16 v[70:73], v[190:193], v[222:225], v[70:73]
	v_mfma_f32_16x16x32_bf16 v[122:125], v[186:189], v[202:205], v[122:125]
	v_mfma_f32_16x16x32_bf16 v[118:121], v[194:197], v[202:205], v[118:121]
	v_mfma_f32_16x16x32_bf16 v[106:109], v[186:189], v[210:213], v[106:109]
	v_mfma_f32_16x16x32_bf16 v[102:105], v[194:197], v[210:213], v[102:105]
	v_mfma_f32_16x16x32_bf16 v[90:93], v[186:189], v[218:221], v[90:93]
	v_mfma_f32_16x16x32_bf16 v[86:89], v[194:197], v[218:221], v[86:89]
	v_mfma_f32_16x16x32_bf16 v[74:77], v[186:189], v[226:229], v[74:77]
	v_mfma_f32_16x16x32_bf16 v[70:73], v[194:197], v[226:229], v[70:73]
	s_setprio 0
	v_lshl_add_u64 v[162:163], v[162:163], 0, s[8:9]
	v_lshl_add_u64 v[230:231], v[230:231], 0, s[8:9]
	v_lshl_add_u64 v[232:233], v[232:233], 0, s[8:9]
	v_lshl_add_u64 v[234:235], v[234:235], 0, s[8:9]
	v_lshl_add_u64 v[236:237], v[236:237], 0, s[8:9]
	v_lshl_add_u64 v[238:239], v[238:239], 0, s[8:9]
	s_add_i32 s44, s44, s94
	s_barrier
; #define PG8_STAGE(bufoff, gbase, voff) do { _Pragma("unroll") for (int _i = 0; _i < 2; ++_i) \
;         __builtin_amdgcn_global_load_lds((const unsigned*)((const char*)(gbase) + (voff)[_i]), (LAS unsigned*)(lds + (bufoff) + ldsw + _i * 8192), 16, 0, 0); } while (0)
; #define PG8_LDA(dst, b, h) do { _Pragma("unroll") for (int m = 0; m < 4; ++m) _Pragma("unroll") for (int k = 0; k < 2; ++k) dst[m][k] = *(const LAS bf16x8*)(lds + PG8_SA(b, h) + aoff + m * 2048 + k * 1024); } while (0)
; #define PG8_MMA(ai, bj, At, Bt) do { __builtin_amdgcn_s_setprio(1); _Pragma("unroll") for (int m = 0; m < 4; ++m) _Pragma("unroll") for (int n = 0; n < 2; ++n) _Pragma("unroll") for (int k = 0; k < 2; ++k) \
;         acc[ai][bj][m][n] = __builtin_amdgcn_mfma_f32_16x16x32_bf16(Bt[n][k], At[m][k], acc[ai][bj][m][n], 0, 0, 0); __builtin_amdgcn_s_setprio(0); } while (0)
; #define PG8_WAIT_V(n) asm volatile("s_waitcnt vmcnt(" #n ")" ::: "memory")
; #define PG8_WAIT_L(n) asm volatile("s_waitcnt lgkmcnt(" #n ")" ::: "memory")
; #define PG8_BAR __builtin_amdgcn_s_barrier()
; #define PG8_SCHED __builtin_amdgcn_sched_barrier(0)
; template <bool ALIGN_EPI, bool SP2, class Epi, class Sched>
; __device__ __forceinline__ void gemm_phase(LAS unsigned char* lds, const Gemm g, const Sched& S, const Epi& E) {
;     ...
;         for (int t = 0; t < nt; t += 2) {
;             const bool last = (t == nt - 2);
;             const char* a1 = cA + (size_t)(t + 1) * kstep;
;             const char* a2 = last ? nA : cA + (size_t)(t + 2) * kstep; const char* b2 = last ? nB : cB + (size_t)(t + 2) * kstep;
;             const char* a3 = a2 + kstep; const char* b3 = b2 + kstep;
;     ...
;             PG8_STAGE(PG8_SB(1, 0), b3, voffB); PG8_STAGE(PG8_SB(1, 1), b3 + hstep, voffB); PG8_STAGE(PG8_SA(1, 0), a3, voffA); PG8_SCHED; PG8_LDA(At, 1, 1);
;             PG8_WAIT_V(8); PG8_WAIT_L(0); PG8_BAR; PG8_MMA(1, 0, At, B0); PG8_MMA(1, 1, At, B1); PG8_BAR; PG8_SCHED;
	s_mov_b32 m0, s44
	s_nop 0
	global_load_lds_dwordx4 v[162:163], off
	s_add_i32 m0, s44, 0x2000
	s_add_i32 s44, s45, s94
	global_load_lds_dwordx4 v[230:231], off
	s_mov_b32 m0, s44
	s_nop 0
	global_load_lds_dwordx4 v[232:233], off
	s_add_i32 m0, s44, 0x2000
	s_nop 0
	global_load_lds_dwordx4 v[234:235], off
	s_mov_b32 m0, s62
	s_nop 0
	global_load_lds_dwordx4 v[236:237], off
	s_mov_b32 m0, s63
	s_nop 0
	global_load_lds_dwordx4 v[238:239], off
	ds_read_b128 v[198:201], v176 offset:49152
	ds_read_b128 v[202:205], v176 offset:50176
	ds_read_b128 v[206:209], v176 offset:51200
	ds_read_b128 v[210:213], v176 offset:52224
	ds_read_b128 v[214:217], v176 offset:53248
	ds_read_b128 v[218:221], v176 offset:54272
	ds_read_b128 v[222:225], v176 offset:55296
	ds_read_b128 v[226:229], v176 offset:56320
	s_waitcnt vmcnt(8)
	s_waitcnt lgkmcnt(0)
	s_barrier
	s_setprio 1
	s_waitcnt lgkmcnt(0)
	v_mfma_f32_16x16x32_bf16 v[50:53], v[150:153], v[198:201], v[50:53]
	v_mfma_f32_16x16x32_bf16 v[62:65], v[158:161], v[198:201], v[62:65]
	v_mfma_f32_16x16x32_bf16 v[34:37], v[150:153], v[206:209], v[34:37]
	v_mfma_f32_16x16x32_bf16 v[46:49], v[158:161], v[206:209], v[46:49]
	v_mfma_f32_16x16x32_bf16 v[18:21], v[150:153], v[214:217], v[18:21]
	v_mfma_f32_16x16x32_bf16 v[30:33], v[158:161], v[214:217], v[30:33]
	v_mfma_f32_16x16x32_bf16 v[2:5], v[150:153], v[222:225], v[2:5]
	v_mfma_f32_16x16x32_bf16 v[14:17], v[158:161], v[222:225], v[14:17]
	v_mfma_f32_16x16x32_bf16 v[50:53], v[154:157], v[202:205], v[50:53]
	v_mfma_f32_16x16x32_bf16 v[62:65], v[178:181], v[202:205], v[62:65]
	v_mfma_f32_16x16x32_bf16 v[34:37], v[154:157], v[210:213], v[34:37]
	v_mfma_f32_16x16x32_bf16 v[46:49], v[178:181], v[210:213], v[46:49]
	v_mfma_f32_16x16x32_bf16 v[18:21], v[154:157], v[218:221], v[18:21]
	v_mfma_f32_16x16x32_bf16 v[30:33], v[178:181], v[218:221], v[30:33]
	v_mfma_f32_16x16x32_bf16 v[2:5], v[154:157], v[226:229], v[2:5]
	v_mfma_f32_16x16x32_bf16 v[14:17], v[178:181], v[226:229], v[14:17]
	s_setprio 0
	s_setprio 1
	v_mfma_f32_16x16x32_bf16 v[58:61], v[182:185], v[198:201], v[58:61]
	v_mfma_f32_16x16x32_bf16 v[54:57], v[190:193], v[198:201], v[54:57]
	v_mfma_f32_16x16x32_bf16 v[42:45], v[182:185], v[206:209], v[42:45]
	v_mfma_f32_16x16x32_bf16 v[38:41], v[190:193], v[206:209], v[38:41]
	v_mfma_f32_16x16x32_bf16 v[26:29], v[182:185], v[214:217], v[26:29]
	v_mfma_f32_16x16x32_bf16 v[22:25], v[190:193], v[214:217], v[22:25]
	v_mfma_f32_16x16x32_bf16 v[10:13], v[182:185], v[222:225], v[10:13]
	v_mfma_f32_16x16x32_bf16 v[6:9], v[190:193], v[222:225], v[6:9]
	v_mfma_f32_16x16x32_bf16 v[58:61], v[186:189], v[202:205], v[58:61]
	v_mfma_f32_16x16x32_bf16 v[54:57], v[194:197], v[202:205], v[54:57]
	v_mfma_f32_16x16x32_bf16 v[42:45], v[186:189], v[210:213], v[42:45]
	v_mfma_f32_16x16x32_bf16 v[38:41], v[194:197], v[210:213], v[38:41]
	v_mfma_f32_16x16x32_bf16 v[26:29], v[186:189], v[218:221], v[26:29]
	v_mfma_f32_16x16x32_bf16 v[22:25], v[194:197], v[218:221], v[22:25]
	v_mfma_f32_16x16x32_bf16 v[10:13], v[186:189], v[226:229], v[10:13]
	v_mfma_f32_16x16x32_bf16 v[6:9], v[194:197], v[226:229], v[6:9]
	s_setprio 0
	s_add_u32 s42, s42, 0x100
	s_addc_u32 s43, s43, 0
	s_add_u32 s24, s24, 0x100
	s_addc_u32 s71, s71, 0
	v_lshl_add_u64 v[162:163], s[42:43], 0, v[138:139]
	v_lshl_add_u64 v[230:231], s[42:43], 0, v[148:149]
	s_cmp_ge_i32 s88, s64
	s_mov_b32 s44, s88
	s_barrier
	s_cbranch_scc0 .LBB0_235
